# attnB loop edge: rescale test inverted so the common path falls through; next-tile exps finished two MFMA gaps before the barrier
# speedup vs baseline: 1.0074x; 1.0026x over previous
.Lb_loop:
	s_waitcnt lgkmcnt(0)
	v_mfma_f32_32x32x16_bf16 v[32:47], v[192:195], v[224:227], v[32:47]
	v_mfma_f32_32x32x16_bf16 v[48:63], v[196:199], v[224:227], v[48:63]
	ds_read_b128 v[96:99], v146 offset:33280
	ds_read_b128 v[100:103], v147 offset:33280
	ds_read_b128 v[104:107], v148 offset:33280
	ds_read_b128 v[108:111], v149 offset:33280
	v_mfma_f32_32x32x16_bf16 v[16:31], v[200:203], v[224:227], v[16:31]
	v_exp_f32_e32 v240, v80
	v_exp_f32_e32 v241, v81
	v_exp_f32_e32 v242, v82
	v_mfma_f32_32x32x16_bf16 v[0:15], v[204:207], v[224:227], v[0:15]
	v_exp_f32_e32 v243, v83
	v_exp_f32_e32 v244, v84
	v_exp_f32_e32 v245, v85
	s_waitcnt lgkmcnt(0)
	v_mfma_f32_32x32x16_bf16 v[112:127], v[96:99], v[128:131], v[64:79]
	ds_read_b128 v[96:99], v146 offset:37376
	ds_read_b64_tr_b16 v[192:193], v179 offset:18688
	ds_read_b64_tr_b16 v[194:195], v179 offset:19200
	v_add_f32_e32 v145, v240, v241
	v_cvt_pk_bf16_f32 v232, v240, v241
	v_exp_f32_e32 v246, v86
	v_exp_f32_e32 v247, v87
	v_mfma_f32_32x32x16_bf16 v[112:127], v[100:103], v[132:135], v[112:127]
	ds_read_b128 v[100:103], v147 offset:37376
	ds_read_b64_tr_b16 v[196:197], v179 offset:22848
	ds_read_b64_tr_b16 v[198:199], v179 offset:23360
	s_add_i32 s0, s50, 0xffff8000
	s_and_b32 s0, s0, 0x1f8000
	s_lshl_b32 s4, s0, 1
	s_add_i32 m0, s41, 0x18600
	s_nop 0
	buffer_load_dwordx4 v250, s[8:11], s4 offen lds
	s_add_i32 m0, s41, 0x1a600
	s_nop 0
	buffer_load_dwordx4 v250, s[8:11], s4 offen offset:128 lds
	v_add_f32_e32 v145, v145, v242
	v_add_f32_e32 v145, v145, v243
	v_cvt_pk_bf16_f32 v233, v242, v243
	v_exp_f32_e32 v240, v88
	v_mfma_f32_32x32x16_bf16 v[112:127], v[104:107], v[136:139], v[112:127]
	ds_read_b128 v[104:107], v148 offset:37376
	ds_read_b64_tr_b16 v[200:201], v179 offset:27008
	ds_read_b64_tr_b16 v[202:203], v179 offset:27520
	v_exp_f32_e32 v241, v89
	v_add_f32_e32 v145, v145, v244
	v_add_f32_e32 v145, v145, v245
	v_cvt_pk_bf16_f32 v234, v244, v245
	v_exp_f32_e32 v242, v90
	v_mfma_f32_32x32x16_bf16 v[112:127], v[108:111], v[140:143], v[112:127]
	ds_read_b128 v[108:111], v149 offset:37376
	ds_read_b64_tr_b16 v[204:205], v179 offset:31168
	ds_read_b64_tr_b16 v[206:207], v179 offset:31680
	s_add_i32 m0, s43, 0x18600
	s_nop 0
	buffer_load_dwordx4 v251, s[12:15], s4 offen lds
	s_add_i32 m0, s43, 0x1a600
	s_nop 0
	buffer_load_dwordx4 v251, s[12:15], s4 offen offset:128 lds
	v_exp_f32_e32 v243, v91
	v_add_f32_e32 v145, v145, v246
	v_add_f32_e32 v145, v145, v247
	v_cvt_pk_bf16_f32 v235, v246, v247
	v_mfma_f32_32x32x16_bf16 v[32:47], v[208:211], v[228:231], v[32:47]
	ds_read_b64_tr_b16 v[208:209], v179 offset:19712
	ds_read_b64_tr_b16 v[210:211], v179 offset:20224
	v_exp_f32_e32 v244, v92
	v_exp_f32_e32 v245, v93
	v_add_f32_e32 v145, v145, v240
	v_add_f32_e32 v145, v145, v241
	v_mfma_f32_32x32x16_bf16 v[48:63], v[212:215], v[228:231], v[48:63]
	ds_read_b64_tr_b16 v[212:213], v179 offset:23872
	ds_read_b64_tr_b16 v[214:215], v179 offset:24384
	v_cvt_pk_bf16_f32 v236, v240, v241
	v_exp_f32_e32 v246, v94
	v_exp_f32_e32 v247, v95
	v_mfma_f32_32x32x16_bf16 v[16:31], v[216:219], v[228:231], v[16:31]
	ds_read_b64_tr_b16 v[216:217], v179 offset:28032
	ds_read_b64_tr_b16 v[218:219], v179 offset:28544
	v_add_f32_e32 v145, v145, v242
	v_add_f32_e32 v145, v145, v243
	v_cvt_pk_bf16_f32 v237, v242, v243
	v_add_f32_e32 v145, v145, v244
	v_add_f32_e32 v145, v145, v245
	v_cvt_pk_bf16_f32 v238, v244, v245
	v_mfma_f32_32x32x16_bf16 v[0:15], v[220:223], v[228:231], v[0:15]
	ds_read_b64_tr_b16 v[220:221], v179 offset:32192
	ds_read_b64_tr_b16 v[222:223], v179 offset:32704
	v_add_f32_e32 v145, v145, v246
	v_add_f32_e32 v249, v145, v247
	v_cvt_pk_bf16_f32 v239, v246, v247
	v_add_f32_e32 v249, v248, v249
	v_cmp_lt_f32_e32 vcc, s3, v249
	v_add_f32_e32 v191, v191, v249
	s_waitcnt lgkmcnt(8)
	v_mfma_f32_32x32x16_bf16 v[80:95], v[96:99], v[128:131], v[64:79]
	v_exp_f32_e32 v240, v112
	v_exp_f32_e32 v241, v113
	v_exp_f32_e32 v242, v114
	v_mfma_f32_32x32x16_bf16 v[80:95], v[100:103], v[132:135], v[80:95]
	v_exp_f32_e32 v243, v115
	v_exp_f32_e32 v244, v116
	v_exp_f32_e32 v245, v117
	v_mfma_f32_32x32x16_bf16 v[80:95], v[104:107], v[136:139], v[80:95]
	v_add_f32_e32 v145, v240, v241
	v_cvt_pk_bf16_f32 v224, v240, v241
	v_exp_f32_e32 v246, v118
	v_mfma_f32_32x32x16_bf16 v[80:95], v[108:111], v[140:143], v[80:95]
	v_exp_f32_e32 v247, v119
	v_add_f32_e32 v145, v145, v242
	v_add_f32_e32 v145, v145, v243
	v_cvt_pk_bf16_f32 v225, v242, v243
	v_exp_f32_e32 v240, v120
	v_mfma_f32_32x32x16_bf16 v[32:47], v[192:195], v[232:235], v[32:47]
	ds_read_b64_tr_b16 v[192:193], v180 offset:0
	ds_read_b64_tr_b16 v[194:195], v180 offset:512
	v_exp_f32_e32 v241, v121
	v_add_f32_e32 v145, v145, v244
	v_add_f32_e32 v145, v145, v245
	v_cvt_pk_bf16_f32 v226, v244, v245
	v_mfma_f32_32x32x16_bf16 v[48:63], v[196:199], v[232:235], v[48:63]
	ds_read_b64_tr_b16 v[196:197], v180 offset:4160
	ds_read_b64_tr_b16 v[198:199], v180 offset:4672
	v_exp_f32_e32 v242, v122
	v_exp_f32_e32 v243, v123
	v_add_f32_e32 v145, v145, v246
	v_mfma_f32_32x32x16_bf16 v[16:31], v[200:203], v[232:235], v[16:31]
	ds_read_b64_tr_b16 v[200:201], v180 offset:8320
	ds_read_b64_tr_b16 v[202:203], v180 offset:8832
	v_add_f32_e32 v145, v145, v247
	v_cvt_pk_bf16_f32 v227, v246, v247
	v_exp_f32_e32 v244, v124
	v_exp_f32_e32 v245, v125
	v_mfma_f32_32x32x16_bf16 v[0:15], v[204:207], v[232:235], v[0:15]
	ds_read_b64_tr_b16 v[204:205], v180 offset:12480
	ds_read_b64_tr_b16 v[206:207], v180 offset:12992
	v_add_f32_e32 v145, v145, v240
	v_add_f32_e32 v145, v145, v241
	v_cvt_pk_bf16_f32 v228, v240, v241
	v_exp_f32_e32 v246, v126
	s_waitcnt lgkmcnt(8)
	v_mfma_f32_32x32x16_bf16 v[32:47], v[208:211], v[236:239], v[32:47]
	ds_read_b64_tr_b16 v[208:209], v180 offset:1024
	ds_read_b64_tr_b16 v[210:211], v180 offset:1536
	v_exp_f32_e32 v247, v127
	v_add_f32_e32 v145, v145, v242
	v_add_f32_e32 v145, v145, v243
	v_cvt_pk_bf16_f32 v229, v242, v243
	v_add_f32_e32 v145, v145, v244
	v_mfma_f32_32x32x16_bf16 v[48:63], v[212:215], v[236:239], v[48:63]
	ds_read_b64_tr_b16 v[212:213], v180 offset:5184
	ds_read_b64_tr_b16 v[214:215], v180 offset:5696
	v_add_f32_e32 v145, v145, v245
	v_cvt_pk_bf16_f32 v230, v244, v245
	v_add_f32_e32 v145, v145, v246
	v_add_f32_e32 v248, v145, v247
	v_cvt_pk_bf16_f32 v231, v246, v247
	v_mfma_f32_32x32x16_bf16 v[16:31], v[216:219], v[236:239], v[16:31]
	ds_read_b64_tr_b16 v[216:217], v180 offset:9344
	ds_read_b64_tr_b16 v[218:219], v180 offset:9856
	v_mfma_f32_32x32x16_bf16 v[0:15], v[220:223], v[236:239], v[0:15]
	ds_read_b64_tr_b16 v[220:221], v180 offset:13504
	ds_read_b64_tr_b16 v[222:223], v180 offset:14016
	s_cbranch_vccnz .Lb_rare0

.Lb_pn3:
	v_exp_f32_e32 v243, v91
	v_add_f32_e32 v145, v145, v246
	v_add_f32_e32 v145, v145, v247
	v_cvt_pk_bf16_f32 v235, v246, v247
	v_mfma_f32_32x32x16_bf16 v[32:47], v[208:211], v[228:231], v[32:47]
	ds_read_b64_tr_b16 v[208:209], v180 offset:3072
	ds_read_b64_tr_b16 v[210:211], v180 offset:3584
	v_exp_f32_e32 v244, v92
	v_exp_f32_e32 v245, v93
	v_add_f32_e32 v145, v145, v240
	v_add_f32_e32 v145, v145, v241
	v_mfma_f32_32x32x16_bf16 v[48:63], v[212:215], v[228:231], v[48:63]
	ds_read_b64_tr_b16 v[212:213], v180 offset:7232
	ds_read_b64_tr_b16 v[214:215], v180 offset:7744
	v_cvt_pk_bf16_f32 v236, v240, v241
	v_exp_f32_e32 v246, v94
	v_exp_f32_e32 v247, v95
	v_mfma_f32_32x32x16_bf16 v[16:31], v[216:219], v[228:231], v[16:31]
	ds_read_b64_tr_b16 v[216:217], v180 offset:11392
	ds_read_b64_tr_b16 v[218:219], v180 offset:11904
	v_add_f32_e32 v145, v145, v242
	v_add_f32_e32 v145, v145, v243
	v_cvt_pk_bf16_f32 v237, v242, v243
	v_add_f32_e32 v145, v145, v244
	v_add_f32_e32 v145, v145, v245
	v_cvt_pk_bf16_f32 v238, v244, v245
	v_mfma_f32_32x32x16_bf16 v[0:15], v[220:223], v[228:231], v[0:15]
	ds_read_b64_tr_b16 v[220:221], v180 offset:15552
	ds_read_b64_tr_b16 v[222:223], v180 offset:16064
	v_add_f32_e32 v145, v145, v246
	v_add_f32_e32 v249, v145, v247
	v_cvt_pk_bf16_f32 v239, v246, v247
	v_add_f32_e32 v249, v248, v249
	v_cmp_lt_f32_e32 vcc, s3, v249
	v_add_f32_e32 v191, v191, v249
	s_waitcnt lgkmcnt(8)
	v_mfma_f32_32x32x16_bf16 v[80:95], v[96:99], v[128:131], v[64:79]
	v_exp_f32_e32 v240, v112
	v_exp_f32_e32 v241, v113
	v_exp_f32_e32 v242, v114
	v_mfma_f32_32x32x16_bf16 v[80:95], v[100:103], v[132:135], v[80:95]
	v_exp_f32_e32 v243, v115
	v_exp_f32_e32 v244, v116
	v_exp_f32_e32 v245, v117
	v_mfma_f32_32x32x16_bf16 v[80:95], v[104:107], v[136:139], v[80:95]
	v_add_f32_e32 v145, v240, v241
	v_cvt_pk_bf16_f32 v224, v240, v241
	v_exp_f32_e32 v246, v118
	v_mfma_f32_32x32x16_bf16 v[80:95], v[108:111], v[140:143], v[80:95]
	v_exp_f32_e32 v247, v119
	v_add_f32_e32 v145, v145, v242
	v_add_f32_e32 v145, v145, v243
	v_cvt_pk_bf16_f32 v225, v242, v243
	v_exp_f32_e32 v240, v120
	v_mfma_f32_32x32x16_bf16 v[32:47], v[192:195], v[232:235], v[32:47]
	ds_read_b64_tr_b16 v[192:193], v182 offset:0
	ds_read_b64_tr_b16 v[194:195], v182 offset:512
	v_exp_f32_e32 v241, v121
	v_add_f32_e32 v145, v145, v244
	v_add_f32_e32 v145, v145, v245
	v_cvt_pk_bf16_f32 v226, v244, v245
	v_mfma_f32_32x32x16_bf16 v[48:63], v[196:199], v[232:235], v[48:63]
	ds_read_b64_tr_b16 v[196:197], v182 offset:4160
	ds_read_b64_tr_b16 v[198:199], v182 offset:4672
	v_exp_f32_e32 v242, v122
	v_exp_f32_e32 v243, v123
	v_add_f32_e32 v145, v145, v246
	v_mfma_f32_32x32x16_bf16 v[16:31], v[200:203], v[232:235], v[16:31]
	ds_read_b64_tr_b16 v[200:201], v182 offset:8320
	ds_read_b64_tr_b16 v[202:203], v182 offset:8832
	v_add_f32_e32 v145, v145, v247
	v_cvt_pk_bf16_f32 v227, v246, v247
	v_exp_f32_e32 v244, v124
	v_exp_f32_e32 v245, v125
	v_mfma_f32_32x32x16_bf16 v[0:15], v[204:207], v[232:235], v[0:15]
	ds_read_b64_tr_b16 v[204:205], v182 offset:12480
	ds_read_b64_tr_b16 v[206:207], v182 offset:12992
	v_add_f32_e32 v145, v145, v240
	v_add_f32_e32 v145, v145, v241
	v_cvt_pk_bf16_f32 v228, v240, v241
	v_exp_f32_e32 v246, v126
	s_waitcnt lgkmcnt(8)
	v_mfma_f32_32x32x16_bf16 v[32:47], v[208:211], v[236:239], v[32:47]
	ds_read_b64_tr_b16 v[208:209], v182 offset:1024
	ds_read_b64_tr_b16 v[210:211], v182 offset:1536
	v_exp_f32_e32 v247, v127
	v_add_f32_e32 v145, v145, v242
	v_add_f32_e32 v145, v145, v243
	v_cvt_pk_bf16_f32 v229, v242, v243
	v_add_f32_e32 v145, v145, v244
	v_mfma_f32_32x32x16_bf16 v[48:63], v[212:215], v[236:239], v[48:63]
	ds_read_b64_tr_b16 v[212:213], v182 offset:5184
	ds_read_b64_tr_b16 v[214:215], v182 offset:5696
	v_add_f32_e32 v145, v145, v245
	v_cvt_pk_bf16_f32 v230, v244, v245
	v_add_f32_e32 v145, v145, v246
	v_add_f32_e32 v248, v145, v247
	v_cvt_pk_bf16_f32 v231, v246, v247
	v_mfma_f32_32x32x16_bf16 v[16:31], v[216:219], v[236:239], v[16:31]
	ds_read_b64_tr_b16 v[216:217], v182 offset:9344
	ds_read_b64_tr_b16 v[218:219], v182 offset:9856
	v_mfma_f32_32x32x16_bf16 v[0:15], v[220:223], v[236:239], v[0:15]
	ds_read_b64_tr_b16 v[220:221], v182 offset:13504
	ds_read_b64_tr_b16 v[222:223], v182 offset:14016
	s_cbranch_vccnz .Lb_rare1

.Lb_pn7:
	v_exp_f32_e32 v243, v91
	v_add_f32_e32 v145, v145, v246
	v_add_f32_e32 v145, v145, v247
	v_cvt_pk_bf16_f32 v235, v246, v247
	v_mfma_f32_32x32x16_bf16 v[32:47], v[208:211], v[228:231], v[32:47]
	ds_read_b64_tr_b16 v[208:209], v182 offset:3072
	ds_read_b64_tr_b16 v[210:211], v182 offset:3584
	v_exp_f32_e32 v244, v92
	v_exp_f32_e32 v245, v93
	v_add_f32_e32 v145, v145, v240
	v_add_f32_e32 v145, v145, v241
	v_mfma_f32_32x32x16_bf16 v[48:63], v[212:215], v[228:231], v[48:63]
	ds_read_b64_tr_b16 v[212:213], v182 offset:7232
	ds_read_b64_tr_b16 v[214:215], v182 offset:7744
	v_cvt_pk_bf16_f32 v236, v240, v241
	v_exp_f32_e32 v246, v94
	v_exp_f32_e32 v247, v95
	v_mfma_f32_32x32x16_bf16 v[16:31], v[216:219], v[228:231], v[16:31]
	ds_read_b64_tr_b16 v[216:217], v182 offset:11392
	ds_read_b64_tr_b16 v[218:219], v182 offset:11904
	v_add_f32_e32 v145, v145, v242
	v_add_f32_e32 v145, v145, v243
	v_cvt_pk_bf16_f32 v237, v242, v243
	v_add_f32_e32 v145, v145, v244
	v_add_f32_e32 v145, v145, v245
	v_cvt_pk_bf16_f32 v238, v244, v245
	v_mfma_f32_32x32x16_bf16 v[0:15], v[220:223], v[228:231], v[0:15]
	ds_read_b64_tr_b16 v[220:221], v182 offset:15552
	ds_read_b64_tr_b16 v[222:223], v182 offset:16064
	v_add_f32_e32 v145, v145, v246
	v_add_f32_e32 v249, v145, v247
	v_cvt_pk_bf16_f32 v239, v246, v247
	v_add_f32_e32 v249, v248, v249
	v_cmp_lt_f32_e32 vcc, s3, v249
	v_add_f32_e32 v191, v191, v249
	s_waitcnt lgkmcnt(8)
	v_mfma_f32_32x32x16_bf16 v[80:95], v[96:99], v[128:131], v[64:79]
	v_exp_f32_e32 v240, v112
	v_exp_f32_e32 v241, v113
	v_exp_f32_e32 v242, v114
	v_mfma_f32_32x32x16_bf16 v[80:95], v[100:103], v[132:135], v[80:95]
	v_exp_f32_e32 v243, v115
	v_exp_f32_e32 v244, v116
	v_exp_f32_e32 v245, v117
	v_mfma_f32_32x32x16_bf16 v[80:95], v[104:107], v[136:139], v[80:95]
	v_add_f32_e32 v145, v240, v241
	v_cvt_pk_bf16_f32 v224, v240, v241
	v_exp_f32_e32 v246, v118
	v_mfma_f32_32x32x16_bf16 v[80:95], v[108:111], v[140:143], v[80:95]
	v_exp_f32_e32 v247, v119
	v_add_f32_e32 v145, v145, v242
	v_add_f32_e32 v145, v145, v243
	v_cvt_pk_bf16_f32 v225, v242, v243
	v_exp_f32_e32 v240, v120
	v_mfma_f32_32x32x16_bf16 v[32:47], v[192:195], v[232:235], v[32:47]
	ds_read_b64_tr_b16 v[192:193], v182 offset:33280
	ds_read_b64_tr_b16 v[194:195], v182 offset:33792
	v_exp_f32_e32 v241, v121
	v_add_f32_e32 v145, v145, v244
	v_add_f32_e32 v145, v145, v245
	v_cvt_pk_bf16_f32 v226, v244, v245
	v_mfma_f32_32x32x16_bf16 v[48:63], v[196:199], v[232:235], v[48:63]
	ds_read_b64_tr_b16 v[196:197], v182 offset:37440
	ds_read_b64_tr_b16 v[198:199], v182 offset:37952
	v_exp_f32_e32 v242, v122
	v_exp_f32_e32 v243, v123
	v_add_f32_e32 v145, v145, v246
	v_mfma_f32_32x32x16_bf16 v[16:31], v[200:203], v[232:235], v[16:31]
	ds_read_b64_tr_b16 v[200:201], v182 offset:41600
	ds_read_b64_tr_b16 v[202:203], v182 offset:42112
	v_add_f32_e32 v145, v145, v247
	v_cvt_pk_bf16_f32 v227, v246, v247
	v_exp_f32_e32 v244, v124
	v_exp_f32_e32 v245, v125
	v_mfma_f32_32x32x16_bf16 v[0:15], v[204:207], v[232:235], v[0:15]
	ds_read_b64_tr_b16 v[204:205], v182 offset:45760
	ds_read_b64_tr_b16 v[206:207], v182 offset:46272
	v_add_f32_e32 v145, v145, v240
	v_add_f32_e32 v145, v145, v241
	v_cvt_pk_bf16_f32 v228, v240, v241
	v_exp_f32_e32 v246, v126
	s_waitcnt lgkmcnt(8)
	v_mfma_f32_32x32x16_bf16 v[32:47], v[208:211], v[236:239], v[32:47]
	ds_read_b64_tr_b16 v[208:209], v182 offset:34304
	ds_read_b64_tr_b16 v[210:211], v182 offset:34816
	v_exp_f32_e32 v247, v127
	v_add_f32_e32 v145, v145, v242
	v_add_f32_e32 v145, v145, v243
	v_cvt_pk_bf16_f32 v229, v242, v243
	v_add_f32_e32 v145, v145, v244
	v_mfma_f32_32x32x16_bf16 v[48:63], v[212:215], v[236:239], v[48:63]
	ds_read_b64_tr_b16 v[212:213], v182 offset:38464
	ds_read_b64_tr_b16 v[214:215], v182 offset:38976
	v_add_f32_e32 v145, v145, v245
	v_cvt_pk_bf16_f32 v230, v244, v245
	v_add_f32_e32 v145, v145, v246
	v_add_f32_e32 v248, v145, v247
	v_cvt_pk_bf16_f32 v231, v246, v247
	v_mfma_f32_32x32x16_bf16 v[16:31], v[216:219], v[236:239], v[16:31]
	ds_read_b64_tr_b16 v[216:217], v182 offset:42624
	ds_read_b64_tr_b16 v[218:219], v182 offset:43136
	v_mfma_f32_32x32x16_bf16 v[0:15], v[220:223], v[236:239], v[0:15]
	ds_read_b64_tr_b16 v[220:221], v182 offset:46784
	ds_read_b64_tr_b16 v[222:223], v182 offset:47296
	s_cbranch_vccnz .Lb_rare2
.Lb_cont2:
	s_waitcnt vmcnt(4)
	s_barrier
	s_cmp_gt_u32 s6, 59
	s_cbranch_scc1 .Lb_final
	s_waitcnt lgkmcnt(0)
	v_mfma_f32_32x32x16_bf16 v[32:47], v[192:195], v[224:227], v[32:47]
	v_mfma_f32_32x32x16_bf16 v[48:63], v[196:199], v[224:227], v[48:63]
	ds_read_b128 v[96:99], v146 offset:0
	ds_read_b128 v[100:103], v147 offset:0
	ds_read_b128 v[104:107], v148 offset:0
	ds_read_b128 v[108:111], v149 offset:0
	v_mfma_f32_32x32x16_bf16 v[16:31], v[200:203], v[224:227], v[16:31]
	v_exp_f32_e32 v240, v80
	v_exp_f32_e32 v241, v81
	v_exp_f32_e32 v242, v82
	v_mfma_f32_32x32x16_bf16 v[0:15], v[204:207], v[224:227], v[0:15]
	v_exp_f32_e32 v243, v83
	v_exp_f32_e32 v244, v84
	v_exp_f32_e32 v245, v85
	s_waitcnt lgkmcnt(0)
	v_mfma_f32_32x32x16_bf16 v[112:127], v[96:99], v[128:131], v[64:79]
	ds_read_b128 v[96:99], v146 offset:4096
	ds_read_b64_tr_b16 v[192:193], v182 offset:35328
	ds_read_b64_tr_b16 v[194:195], v182 offset:35840
	v_add_f32_e32 v145, v240, v241
	v_cvt_pk_bf16_f32 v232, v240, v241
	v_exp_f32_e32 v246, v86
	v_exp_f32_e32 v247, v87
	v_mfma_f32_32x32x16_bf16 v[112:127], v[100:103], v[132:135], v[112:127]
	ds_read_b128 v[100:103], v147 offset:4096
	ds_read_b64_tr_b16 v[196:197], v182 offset:39488
	ds_read_b64_tr_b16 v[198:199], v182 offset:40000
	s_add_i32 s0, s50, 0x10000
	s_and_b32 s0, s0, 0x1f8000
	s_lshl_b32 s4, s0, 1
	s_add_i32 m0, s41, 0x10400
	s_nop 0
	buffer_load_dwordx4 v250, s[8:11], s4 offen lds
	s_add_i32 m0, s41, 0x12400
	s_nop 0
	buffer_load_dwordx4 v250, s[8:11], s4 offen offset:128 lds
	v_add_f32_e32 v145, v145, v242
	v_add_f32_e32 v145, v145, v243
	v_cvt_pk_bf16_f32 v233, v242, v243
	v_exp_f32_e32 v240, v88
	v_mfma_f32_32x32x16_bf16 v[112:127], v[104:107], v[136:139], v[112:127]
	ds_read_b128 v[104:107], v148 offset:4096
	ds_read_b64_tr_b16 v[200:201], v182 offset:43648
	ds_read_b64_tr_b16 v[202:203], v182 offset:44160
	v_exp_f32_e32 v241, v89
	v_add_f32_e32 v145, v145, v244
	v_add_f32_e32 v145, v145, v245
	v_cvt_pk_bf16_f32 v234, v244, v245
	v_exp_f32_e32 v242, v90
	v_mfma_f32_32x32x16_bf16 v[112:127], v[108:111], v[140:143], v[112:127]
	ds_read_b128 v[108:111], v149 offset:4096
	ds_read_b64_tr_b16 v[204:205], v182 offset:47808
	ds_read_b64_tr_b16 v[206:207], v182 offset:48320
	s_add_i32 m0, s43, 0x10400
	s_nop 0
	buffer_load_dwordx4 v251, s[12:15], s4 offen lds
	s_add_i32 m0, s43, 0x12400
	s_nop 0
	buffer_load_dwordx4 v251, s[12:15], s4 offen offset:128 lds
	v_exp_f32_e32 v243, v91
	v_add_f32_e32 v145, v145, v246
	v_add_f32_e32 v145, v145, v247
	v_cvt_pk_bf16_f32 v235, v246, v247
	v_mfma_f32_32x32x16_bf16 v[32:47], v[208:211], v[228:231], v[32:47]
	ds_read_b64_tr_b16 v[208:209], v182 offset:36352
	ds_read_b64_tr_b16 v[210:211], v182 offset:36864
	v_exp_f32_e32 v244, v92
	v_exp_f32_e32 v245, v93
	v_add_f32_e32 v145, v145, v240
	v_add_f32_e32 v145, v145, v241
	v_mfma_f32_32x32x16_bf16 v[48:63], v[212:215], v[228:231], v[48:63]
	ds_read_b64_tr_b16 v[212:213], v182 offset:40512
	ds_read_b64_tr_b16 v[214:215], v182 offset:41024
	v_cvt_pk_bf16_f32 v236, v240, v241
	v_exp_f32_e32 v246, v94
	v_exp_f32_e32 v247, v95
	v_mfma_f32_32x32x16_bf16 v[16:31], v[216:219], v[228:231], v[16:31]
	ds_read_b64_tr_b16 v[216:217], v182 offset:44672
	ds_read_b64_tr_b16 v[218:219], v182 offset:45184
	v_add_f32_e32 v145, v145, v242
	v_add_f32_e32 v145, v145, v243
	v_cvt_pk_bf16_f32 v237, v242, v243
	v_add_f32_e32 v145, v145, v244
	v_add_f32_e32 v145, v145, v245
	v_cvt_pk_bf16_f32 v238, v244, v245
	v_mfma_f32_32x32x16_bf16 v[0:15], v[220:223], v[228:231], v[0:15]
	ds_read_b64_tr_b16 v[220:221], v182 offset:48832
	ds_read_b64_tr_b16 v[222:223], v182 offset:49344
	v_add_f32_e32 v145, v145, v246
	v_add_f32_e32 v249, v145, v247
	v_cvt_pk_bf16_f32 v239, v246, v247
	v_add_f32_e32 v249, v248, v249
	v_cmp_lt_f32_e32 vcc, s3, v249
	v_add_f32_e32 v191, v191, v249
	s_waitcnt lgkmcnt(8)
	v_mfma_f32_32x32x16_bf16 v[80:95], v[96:99], v[128:131], v[64:79]
	v_exp_f32_e32 v240, v112
	v_exp_f32_e32 v241, v113
	v_exp_f32_e32 v242, v114
	v_mfma_f32_32x32x16_bf16 v[80:95], v[100:103], v[132:135], v[80:95]
	v_exp_f32_e32 v243, v115
	v_exp_f32_e32 v244, v116
	v_exp_f32_e32 v245, v117
	v_mfma_f32_32x32x16_bf16 v[80:95], v[104:107], v[136:139], v[80:95]
	v_add_f32_e32 v145, v240, v241
	v_cvt_pk_bf16_f32 v224, v240, v241
	v_exp_f32_e32 v246, v118
	v_mfma_f32_32x32x16_bf16 v[80:95], v[108:111], v[140:143], v[80:95]
	v_exp_f32_e32 v247, v119
	v_add_f32_e32 v145, v145, v242
	v_add_f32_e32 v145, v145, v243
	v_cvt_pk_bf16_f32 v225, v242, v243
	v_exp_f32_e32 v240, v120
	v_mfma_f32_32x32x16_bf16 v[32:47], v[192:195], v[232:235], v[32:47]
	ds_read_b64_tr_b16 v[192:193], v179 offset:16640
	ds_read_b64_tr_b16 v[194:195], v179 offset:17152
	v_exp_f32_e32 v241, v121
	v_add_f32_e32 v145, v145, v244
	v_add_f32_e32 v145, v145, v245
	v_cvt_pk_bf16_f32 v226, v244, v245
	v_mfma_f32_32x32x16_bf16 v[48:63], v[196:199], v[232:235], v[48:63]
	ds_read_b64_tr_b16 v[196:197], v179 offset:20800
	ds_read_b64_tr_b16 v[198:199], v179 offset:21312
	v_exp_f32_e32 v242, v122
	v_exp_f32_e32 v243, v123
	v_add_f32_e32 v145, v145, v246
	v_mfma_f32_32x32x16_bf16 v[16:31], v[200:203], v[232:235], v[16:31]
	ds_read_b64_tr_b16 v[200:201], v179 offset:24960
	ds_read_b64_tr_b16 v[202:203], v179 offset:25472
	v_add_f32_e32 v145, v145, v247
	v_cvt_pk_bf16_f32 v227, v246, v247
	v_exp_f32_e32 v244, v124
	v_exp_f32_e32 v245, v125
	v_mfma_f32_32x32x16_bf16 v[0:15], v[204:207], v[232:235], v[0:15]
	ds_read_b64_tr_b16 v[204:205], v179 offset:29120
	ds_read_b64_tr_b16 v[206:207], v179 offset:29632
	v_add_f32_e32 v145, v145, v240
	v_add_f32_e32 v145, v145, v241
	v_cvt_pk_bf16_f32 v228, v240, v241
	v_exp_f32_e32 v246, v126
	s_waitcnt lgkmcnt(8)
	v_mfma_f32_32x32x16_bf16 v[32:47], v[208:211], v[236:239], v[32:47]
	ds_read_b64_tr_b16 v[208:209], v179 offset:17664
	ds_read_b64_tr_b16 v[210:211], v179 offset:18176
	v_exp_f32_e32 v247, v127
	v_add_f32_e32 v145, v145, v242
	v_add_f32_e32 v145, v145, v243
	v_cvt_pk_bf16_f32 v229, v242, v243
	v_add_f32_e32 v145, v145, v244
	v_mfma_f32_32x32x16_bf16 v[48:63], v[212:215], v[236:239], v[48:63]
	ds_read_b64_tr_b16 v[212:213], v179 offset:21824
	ds_read_b64_tr_b16 v[214:215], v179 offset:22336
	v_add_f32_e32 v145, v145, v245
	v_cvt_pk_bf16_f32 v230, v244, v245
	v_add_f32_e32 v145, v145, v246
	v_add_f32_e32 v248, v145, v247
	v_cvt_pk_bf16_f32 v231, v246, v247
	v_mfma_f32_32x32x16_bf16 v[16:31], v[216:219], v[236:239], v[16:31]
	ds_read_b64_tr_b16 v[216:217], v179 offset:25984
	ds_read_b64_tr_b16 v[218:219], v179 offset:26496
	v_mfma_f32_32x32x16_bf16 v[0:15], v[220:223], v[236:239], v[0:15]
	ds_read_b64_tr_b16 v[220:221], v179 offset:30144
	ds_read_b64_tr_b16 v[222:223], v179 offset:30656
	s_cbranch_vccnz .Lb_rare3
